# prep weight transposes (IN/GLU/ATT/O/UP) by hand-written loop with two 32x32 items in flight per wave (replaces compiled one-item loop)
# speedup vs baseline: 1.0171x; 1.0016x over previous
; __device__ __forceinline__ unsigned pk2(float lo, float hi) { f32x2 v = {lo, hi}; bf16v2_t b = __builtin_convertvector(v, bf16v2_t); return __builtin_bit_cast(unsigned, b); }
; template <int MODE>
; __device__ __forceinline__ void transpose_item(const float* __restrict__ W, int K, int N, bf16_t* __restrict__ WT, int HH, float* scr, int item, int lane) {
;   const int nblk = N / 32, kb = item / nblk, nb = item - kb * nblk, k0 = 32 * kb, n0 = 32 * nb;
; #pragma unroll 8
;   for (int i = 0; i < 16; ++i) { const int kk = 2 * i + (lane >> 5); scr[kk * 33 + (lane & 31)] = W[(size_t)(k0 + kk) * N + n0 + (lane & 31)]; }
;   asm volatile("s_waitcnt lgkmcnt(0)" ::: "memory");
;   const int c = lane & 3;
; #pragma unroll
;   for (int j = 0; j < 2; ++j) {
;     const int n = (lane >> 2) + 16 * j; const float* sp = scr + (8 * c) * 33 + n;
;     u32x4 o; o.x = pk2(sp[0], sp[33]); o.y = pk2(sp[66], sp[99]); o.z = pk2(sp[132], sp[165]); o.w = pk2(sp[198], sp[231]);
;     *(u32x4*)(WT + (size_t)dest_row<MODE>(n0 + n, HH) * K + k0 + 8 * c) = o;
; __device__ __forceinline__ void prep_phase(const Params& p, char* lds) {
;     ...
;     float* scr = (float*)(lds + wid * 8704);
;     constexpr int I_IN = 32 * 104, I_GLU = 16 * 64, I_ATT = 16 * 32, I_O = 32 * 32, I_UP = 32 * 176, I_DN = 88 * 32;
;     constexpr int NIT = I_IN + I_GLU + I_ATT + I_O + I_UP + I_DN;
;     for (int it = gw; it < NIT; it += NGW) {
;       int r = it;
;       if (r < I_IN) { transpose_item<0>(p.in[7], 1024, DIN, (bf16_t*)(ws + OFF_WIN), 0, scr, r, lane); continue; } r -= I_IN;
;       if (r < I_GLU) { transpose_item<1>(p.in[16], 512, 2048, (bf16_t*)(ws + OFF_WGLU), 1024, scr, r, lane); continue; } r -= I_GLU;
;       if (r < I_ATT) { transpose_item<0>(p.in[18], 512, 1024, (bf16_t*)(ws + OFF_WATT), 0, scr, r, lane); continue; } r -= I_ATT;
;       if (r < I_O) { transpose_item<0>(p.in[19], 1024, 1024, (bf16_t*)(ws + OFF_WO), 0, scr, r, lane); continue; } r -= I_O;
;       if (r < I_UP) { transpose_item<1>(p.in[22], 1024, 5632, (bf16_t*)(ws + OFF_WUP), DFF, scr, r, lane); continue; } r -= I_UP;
.LBB0_17:
	s_or_b64 exec, exec, s[0:1]
	v_lshrrev_b32_e32 v183, 6, v0
	v_readlane_b32 s0, v244, 33
	v_and_b32_e32 v184, 63, v0
	v_and_b32_e32 v135, 31, v0
	v_lshl_or_b32 v182, s0, 3, v183
	s_lshl_b32 s0, s33, 3
	v_writelane_b32 v244, s0, 51
	v_lshlrev_b32_e32 v43, 3, v0
	v_lshrrev_b32_e32 v134, 3, v0
	v_writelane_b32 v244, s1, 52
	v_writelane_b32 v246, s0, 0
	v_writelane_b32 v246, s1, 1
	v_writelane_b32 v246, s2, 2
	v_writelane_b32 v246, s3, 3
	v_writelane_b32 v246, s4, 4
	v_writelane_b32 v246, s5, 5
	v_writelane_b32 v246, s6, 6
	v_writelane_b32 v246, s7, 7
	v_writelane_b32 v246, s8, 8
	v_writelane_b32 v246, s9, 9
	v_writelane_b32 v246, s10, 10
	v_writelane_b32 v246, s11, 11
	v_writelane_b32 v246, s12, 12
	v_writelane_b32 v246, s13, 13
	v_writelane_b32 v246, s14, 14
	v_writelane_b32 v246, s15, 15
	v_writelane_b32 v246, s16, 16
	v_writelane_b32 v246, s17, 17
	v_writelane_b32 v246, s18, 18
	v_writelane_b32 v246, s19, 19
	v_writelane_b32 v246, s20, 20
	v_writelane_b32 v246, s21, 21
	v_writelane_b32 v246, s22, 22
	v_writelane_b32 v246, s23, 23
	v_writelane_b32 v246, s24, 24
	v_writelane_b32 v246, s25, 25
	v_writelane_b32 v246, s26, 26
	v_writelane_b32 v246, s27, 27
	v_writelane_b32 v246, s28, 28
	v_writelane_b32 v246, s29, 29
	v_writelane_b32 v246, s30, 30
	v_writelane_b32 v246, s31, 31
	v_readlane_b32 s22, v244, 2
	v_readlane_b32 s23, v244, 3
	v_readlane_b32 s20, v244, 33
	v_readfirstlane_b32 s24, v0
	s_nop 3
	s_lshr_b32 s24, s24, 6
	s_lshl_b32 s20, s20, 3
	s_add_u32 s20, s20, s24
	s_lshl_b32 s21, s33, 3
	s_mul_i32 s24, s24, 0x2200
	v_and_b32_e32 v10, 63, v0
	v_lshrrev_b32_e32 v11, 5, v10
	v_and_b32_e32 v12, 31, v10
	v_mul_u32_u24_e32 v13, 33, v11
	v_add_u32_e32 v13, v13, v12
	v_lshl_add_u32 v13, v13, 2, s24
	v_lshlrev_b32_e32 v12, 2, v12
	v_and_b32_e32 v15, 3, v10
	v_lshrrev_b32_e32 v19, 2, v10
	v_mul_u32_u24_e32 v14, 0x108, v15
	v_add_u32_e32 v14, v14, v19
	v_lshl_add_u32 v14, v14, 2, s24
	v_lshlrev_b32_e32 v15, 4, v15
	v_bfe_u32 v16, v10, 4, 1
	v_and_b32_e32 v17, 3, v19
	v_lshl_add_u32 v17, v11, 2, v17
	s_cmpk_lt_u32 s20, 0x2d00
	s_cbranch_scc0 .Lpt_done
.Lpt_loop:
	s_cmpk_lt_u32 s20, 0xd00
	s_cbranch_scc1 .Lpt_A_in
	s_cmpk_lt_u32 s20, 0x1100
	s_cbranch_scc1 .Lpt_A_glu
	s_cmpk_lt_u32 s20, 0x1300
	s_cbranch_scc1 .Lpt_A_att
	s_cmpk_lt_u32 s20, 0x1700
	s_cbranch_scc1 .Lpt_A_o
	s_sub_u32 s26, s20, 0x1700
	s_mul_hi_u32 s27, s26, 0x1745d18
	s_mul_i32 s28, s27, 0xb0
	s_sub_u32 s28, s26, s28
	v_readlane_b32 s0, v244, 47
	v_readlane_b32 s1, v244, 48
	s_mov_b32 s3, 0x5800
	s_movk_i32 s6, 0x800
	s_mov_b32 s29, 0xd180000
	s_movk_i32 s8, 7
	s_movk_i32 s30, 0xb00
	s_movk_i32 s31, 1
	s_branch .Lpt_A_common
.Lpt_A_in:
	s_mov_b32 s26, s20
	s_mul_hi_u32 s27, s26, 0x2762763
	s_mul_i32 s28, s27, 0x68
	s_sub_u32 s28, s26, s28
	v_readlane_b32 s0, v244, 28
	v_readlane_b32 s1, v244, 29
	s_mov_b32 s3, 0x3400
	s_movk_i32 s6, 0x800
	s_mov_b32 s29, 0xc600000
	s_movk_i32 s8, 4
	s_movk_i32 s30, 0x0
	s_movk_i32 s31, 0
	s_branch .Lpt_A_common
.Lpt_A_glu:
	s_sub_u32 s26, s20, 0xd00
	s_lshr_b32 s27, s26, 6
	s_and_b32 s28, s26, 63
	v_readlane_b32 s0, v244, 35
	v_readlane_b32 s1, v244, 36
	s_mov_b32 s3, 0x2000
	s_movk_i32 s6, 0x400
	s_mov_b32 s29, 0xcc80000
	s_movk_i32 s8, 7
	s_movk_i32 s30, 0x400
	s_movk_i32 s31, 1
	s_branch .Lpt_A_common
.Lpt_A_att:
	s_sub_u32 s26, s20, 0x1100
	s_lshr_b32 s27, s26, 5
	s_and_b32 s28, s26, 31
	v_readlane_b32 s0, v244, 39
	v_readlane_b32 s1, v244, 40
	s_mov_b32 s3, 0x1000
	s_movk_i32 s6, 0x400
	s_mov_b32 s29, 0xce80000
	s_movk_i32 s8, 4
	s_movk_i32 s30, 0x0
	s_movk_i32 s31, 0
	s_branch .Lpt_A_common
.Lpt_A_o:
	s_sub_u32 s26, s20, 0x1300
	s_lshr_b32 s27, s26, 5
	s_and_b32 s28, s26, 31
	v_readlane_b32 s0, v244, 41
	v_readlane_b32 s1, v244, 42
	s_mov_b32 s3, 0x1000
	s_movk_i32 s6, 0x800
	s_mov_b32 s29, 0xcf80000
	s_movk_i32 s8, 4
	s_movk_i32 s30, 0x0
	s_movk_i32 s31, 0
	s_branch .Lpt_A_common
.Lpt_A_common:
	s_mul_i32 s25, s27, s3
	s_lshl_b32 s25, s25, 5
	s_lshl_b32 s26, s28, 7
	s_add_u32 s25, s25, s26
	s_add_u32 s0, s0, s25
	s_addc_u32 s1, s1, 0
	v_mad_u32_u24 v3, v11, s3, v12
	s_lshl_b32 s26, s28, 5
	s_cmp_eq_u32 s31, 0
	s_cbranch_scc1 .Lpt_A_m0
	s_cmp_ge_u32 s26, s30
	s_cselect_b32 s25, 1, 0
	s_mul_i32 s31, s25, s30
	s_sub_u32 s26, s26, s31
	s_lshr_b32 s31, s26, 7
	s_lshl_b32 s31, s31, 8
	s_bfe_u32 s26, s26, 0x20005
	s_lshl_b32 s26, s26, 5
	s_add_u32 s26, s31, s26
	s_lshl_b32 s25, s25, 4
	s_add_u32 s26, s26, s25
.Lpt_A_m0:
	s_mul_i32 s26, s26, s6
	s_lshl_b32 s25, s27, 6
	s_add_u32 s26, s26, s25
	s_add_u32 s26, s26, s29
	s_add_u32 s4, s22, s26
	s_addc_u32 s5, s23, 0
	s_lshl_b32 s7, s6, 3
	v_lshlrev_b32_e32 v18, s8, v16
	v_add_u32_e32 v18, v18, v17
	v_mad_u32_u24 v4, v18, s6, v15
	v_add_u32_e32 v5, s7, v4
	s_lshl_b32 s3, s3, 1
	s_add_u32 s9, s20, s21
	s_cmpk_lt_u32 s9, 0x2d00
	s_cselect_b32 s24, 1, 0
	s_cmp_eq_u32 s24, 0
	s_cbranch_scc1 .Lpt_skipdecB
	s_cmpk_lt_u32 s9, 0xd00
	s_cbranch_scc1 .Lpt_B_in
	s_cmpk_lt_u32 s9, 0x1100
	s_cbranch_scc1 .Lpt_B_glu
	s_cmpk_lt_u32 s9, 0x1300
	s_cbranch_scc1 .Lpt_B_att
	s_cmpk_lt_u32 s9, 0x1700
	s_cbranch_scc1 .Lpt_B_o
	s_sub_u32 s26, s9, 0x1700
	s_mul_hi_u32 s27, s26, 0x1745d18
	s_mul_i32 s28, s27, 0xb0
	s_sub_u32 s28, s26, s28
	v_readlane_b32 s10, v244, 47
	v_readlane_b32 s11, v244, 48
	s_mov_b32 s13, 0x5800
	s_movk_i32 s16, 0x800
	s_mov_b32 s29, 0xd180000
	s_movk_i32 s18, 7
	s_movk_i32 s30, 0xb00
	s_movk_i32 s31, 1
	s_branch .Lpt_B_common
; template <int MODE>
; __device__ __forceinline__ void transpose_item(const float* __restrict__ W, int K, int N, bf16_t* __restrict__ WT, int HH, float* scr, int item, int lane) {
;   const int nblk = N / 32, kb = item / nblk, nb = item - kb * nblk, k0 = 32 * kb, n0 = 32 * nb;
; #pragma unroll 8
;   for (int i = 0; i < 16; ++i) { const int kk = 2 * i + (lane >> 5); scr[kk * 33 + (lane & 31)] = W[(size_t)(k0 + kk) * N + n0 + (lane & 31)]; }
.Lpt_B_in:
	s_mov_b32 s26, s9
	s_mul_hi_u32 s27, s26, 0x2762763
	s_mul_i32 s28, s27, 0x68
	s_sub_u32 s28, s26, s28
	v_readlane_b32 s10, v244, 28
	v_readlane_b32 s11, v244, 29
	s_mov_b32 s13, 0x3400
	s_movk_i32 s16, 0x800
	s_mov_b32 s29, 0xc600000
	s_movk_i32 s18, 4
	s_movk_i32 s30, 0x0
	s_movk_i32 s31, 0
	s_branch .Lpt_B_common
.Lpt_B_glu:
	s_sub_u32 s26, s9, 0xd00
	s_lshr_b32 s27, s26, 6
	s_and_b32 s28, s26, 63
	v_readlane_b32 s10, v244, 35
	v_readlane_b32 s11, v244, 36
	s_mov_b32 s13, 0x2000
	s_movk_i32 s16, 0x400
	s_mov_b32 s29, 0xcc80000
	s_movk_i32 s18, 7
	s_movk_i32 s30, 0x400
	s_movk_i32 s31, 1
	s_branch .Lpt_B_common
.Lpt_B_att:
	s_sub_u32 s26, s9, 0x1100
	s_lshr_b32 s27, s26, 5
	s_and_b32 s28, s26, 31
	v_readlane_b32 s10, v244, 39
	v_readlane_b32 s11, v244, 40
	s_mov_b32 s13, 0x1000
	s_movk_i32 s16, 0x400
	s_mov_b32 s29, 0xce80000
	s_movk_i32 s18, 4
	s_movk_i32 s30, 0x0
	s_movk_i32 s31, 0
	s_branch .Lpt_B_common
.Lpt_B_o:
	s_sub_u32 s26, s9, 0x1300
	s_lshr_b32 s27, s26, 5
	s_and_b32 s28, s26, 31
	v_readlane_b32 s10, v244, 41
	v_readlane_b32 s11, v244, 42
	s_mov_b32 s13, 0x1000
	s_movk_i32 s16, 0x800
	s_mov_b32 s29, 0xcf80000
	s_movk_i32 s18, 4
	s_movk_i32 s30, 0x0
	s_movk_i32 s31, 0
	s_branch .Lpt_B_common
.Lpt_B_common:
	s_mul_i32 s25, s27, s13
	s_lshl_b32 s25, s25, 5
	s_lshl_b32 s26, s28, 7
	s_add_u32 s25, s25, s26
	s_add_u32 s10, s10, s25
	s_addc_u32 s11, s11, 0
	v_mad_u32_u24 v6, v11, s13, v12
	s_lshl_b32 s26, s28, 5
	s_cmp_eq_u32 s31, 0
	s_cbranch_scc1 .Lpt_B_m0
	s_cmp_ge_u32 s26, s30
	s_cselect_b32 s25, 1, 0
	s_mul_i32 s31, s25, s30
	s_sub_u32 s26, s26, s31
	s_lshr_b32 s31, s26, 7
	s_lshl_b32 s31, s31, 8
	s_bfe_u32 s26, s26, 0x20005
	s_lshl_b32 s26, s26, 5
	s_add_u32 s26, s31, s26
	s_lshl_b32 s25, s25, 4
	s_add_u32 s26, s26, s25
.Lpt_B_m0:
	s_mul_i32 s26, s26, s16
	s_lshl_b32 s25, s27, 6
	s_add_u32 s26, s26, s25
	s_add_u32 s26, s26, s29
	s_add_u32 s14, s22, s26
	s_addc_u32 s15, s23, 0
	s_lshl_b32 s17, s16, 3
	v_lshlrev_b32_e32 v18, s18, v16
	v_add_u32_e32 v18, v18, v17
	v_mad_u32_u24 v7, v18, s16, v15
	v_add_u32_e32 v8, s17, v7
	s_lshl_b32 s13, s13, 1
.Lpt_skipdecB:
	global_load_dword v44, v3, s[0:1]
	s_add_u32 s0, s0, s3
	s_addc_u32 s1, s1, 0
	global_load_dword v45, v3, s[0:1]
	s_add_u32 s0, s0, s3
	s_addc_u32 s1, s1, 0
	global_load_dword v46, v3, s[0:1]
	s_add_u32 s0, s0, s3
	s_addc_u32 s1, s1, 0
	global_load_dword v47, v3, s[0:1]
	s_add_u32 s0, s0, s3
	s_addc_u32 s1, s1, 0
	global_load_dword v48, v3, s[0:1]
	s_add_u32 s0, s0, s3
	s_addc_u32 s1, s1, 0
	global_load_dword v49, v3, s[0:1]
	s_add_u32 s0, s0, s3
	s_addc_u32 s1, s1, 0
	global_load_dword v50, v3, s[0:1]
	s_add_u32 s0, s0, s3
	s_addc_u32 s1, s1, 0
	global_load_dword v51, v3, s[0:1]
	s_add_u32 s0, s0, s3
	s_addc_u32 s1, s1, 0
	global_load_dword v52, v3, s[0:1]
	s_add_u32 s0, s0, s3
	s_addc_u32 s1, s1, 0
	global_load_dword v53, v3, s[0:1]
	s_add_u32 s0, s0, s3
	s_addc_u32 s1, s1, 0
	global_load_dword v54, v3, s[0:1]
	s_add_u32 s0, s0, s3
	s_addc_u32 s1, s1, 0
	global_load_dword v55, v3, s[0:1]
	s_add_u32 s0, s0, s3
	s_addc_u32 s1, s1, 0
	global_load_dword v56, v3, s[0:1]
	s_add_u32 s0, s0, s3
	s_addc_u32 s1, s1, 0
	global_load_dword v57, v3, s[0:1]
	s_add_u32 s0, s0, s3
	s_addc_u32 s1, s1, 0
	global_load_dword v58, v3, s[0:1]
	s_add_u32 s0, s0, s3
	s_addc_u32 s1, s1, 0
	global_load_dword v59, v3, s[0:1]
	s_cmp_eq_u32 s24, 0
	s_cbranch_scc1 .Lpt_noB1
	global_load_dword v60, v6, s[10:11]
	s_add_u32 s10, s10, s13
	s_addc_u32 s11, s11, 0
	global_load_dword v61, v6, s[10:11]
	s_add_u32 s10, s10, s13
	s_addc_u32 s11, s11, 0
	global_load_dword v62, v6, s[10:11]
	s_add_u32 s10, s10, s13
	s_addc_u32 s11, s11, 0
	global_load_dword v63, v6, s[10:11]
	s_add_u32 s10, s10, s13
	s_addc_u32 s11, s11, 0
	global_load_dword v64, v6, s[10:11]
	s_add_u32 s10, s10, s13
	s_addc_u32 s11, s11, 0
	global_load_dword v65, v6, s[10:11]
	s_add_u32 s10, s10, s13
	s_addc_u32 s11, s11, 0
	global_load_dword v66, v6, s[10:11]
	s_add_u32 s10, s10, s13
	s_addc_u32 s11, s11, 0
	global_load_dword v67, v6, s[10:11]
	s_add_u32 s10, s10, s13
	s_addc_u32 s11, s11, 0
	global_load_dword v68, v6, s[10:11]
	s_add_u32 s10, s10, s13
	s_addc_u32 s11, s11, 0
	global_load_dword v69, v6, s[10:11]
	s_add_u32 s10, s10, s13
	s_addc_u32 s11, s11, 0
	global_load_dword v70, v6, s[10:11]
	s_add_u32 s10, s10, s13
	s_addc_u32 s11, s11, 0
	global_load_dword v71, v6, s[10:11]
	s_add_u32 s10, s10, s13
	s_addc_u32 s11, s11, 0
	global_load_dword v72, v6, s[10:11]
	s_add_u32 s10, s10, s13
	s_addc_u32 s11, s11, 0
	global_load_dword v73, v6, s[10:11]
	s_add_u32 s10, s10, s13
	s_addc_u32 s11, s11, 0
	global_load_dword v74, v6, s[10:11]
	s_add_u32 s10, s10, s13
	s_addc_u32 s11, s11, 0
	global_load_dword v75, v6, s[10:11]
	s_waitcnt vmcnt(16)
	s_branch .Lpt_wA

; __device__ __forceinline__ unsigned pk2(float lo, float hi) { f32x2 v = {lo, hi}; bf16v2_t b = __builtin_convertvector(v, bf16v2_t); return __builtin_bit_cast(unsigned, b); }
; template <int MODE>
; __device__ __forceinline__ void transpose_item(const float* __restrict__ W, int K, int N, bf16_t* __restrict__ WT, int HH, float* scr, int item, int lane) {
;     ...
;   for (int i = 0; i < 16; ++i) { const int kk = 2 * i + (lane >> 5); scr[kk * 33 + (lane & 31)] = W[(size_t)(k0 + kk) * N + n0 + (lane & 31)]; }
;   asm volatile("s_waitcnt lgkmcnt(0)" ::: "memory");
;   const int c = lane & 3;
; #pragma unroll
;   for (int j = 0; j < 2; ++j) {
;     const int n = (lane >> 2) + 16 * j; const float* sp = scr + (8 * c) * 33 + n;
;     u32x4 o; o.x = pk2(sp[0], sp[33]); o.y = pk2(sp[66], sp[99]); o.z = pk2(sp[132], sp[165]); o.w = pk2(sp[198], sp[231]);
;     *(u32x4*)(WT + (size_t)dest_row<MODE>(n0 + n, HH) * K + k0 + 8 * c) = o;
;   }
;   asm volatile("s_waitcnt lgkmcnt(0)" ::: "memory");
.Lpt_wA:
	ds_write_b32 v13, v44 offset:0
	ds_write_b32 v13, v45 offset:264
	ds_write_b32 v13, v46 offset:528
	ds_write_b32 v13, v47 offset:792
	ds_write_b32 v13, v48 offset:1056
	ds_write_b32 v13, v49 offset:1320
	ds_write_b32 v13, v50 offset:1584
	ds_write_b32 v13, v51 offset:1848
	ds_write_b32 v13, v52 offset:2112
	ds_write_b32 v13, v53 offset:2376
	ds_write_b32 v13, v54 offset:2640
	ds_write_b32 v13, v55 offset:2904
	ds_write_b32 v13, v56 offset:3168
	ds_write_b32 v13, v57 offset:3432
	ds_write_b32 v13, v58 offset:3696
	ds_write_b32 v13, v59 offset:3960
	s_cmp_eq_u32 s24, 0
	s_cbranch_scc1 .Lpt_noB2
	s_waitcnt vmcnt(0)
	ds_write_b32 v13, v60 offset:4224
	ds_write_b32 v13, v61 offset:4488
	ds_write_b32 v13, v62 offset:4752
	ds_write_b32 v13, v63 offset:5016
	ds_write_b32 v13, v64 offset:5280
	ds_write_b32 v13, v65 offset:5544
	ds_write_b32 v13, v66 offset:5808
	ds_write_b32 v13, v67 offset:6072
	ds_write_b32 v13, v68 offset:6336
	ds_write_b32 v13, v69 offset:6600
	ds_write_b32 v13, v70 offset:6864
	ds_write_b32 v13, v71 offset:7128
	ds_write_b32 v13, v72 offset:7392
	ds_write_b32 v13, v73 offset:7656
	ds_write_b32 v13, v74 offset:7920
	ds_write_b32 v13, v75 offset:8184
.Lpt_noB2:
	ds_read_b32 v76, v14 offset:0
	ds_read_b32 v77, v14 offset:132
	ds_read_b32 v78, v14 offset:264
	ds_read_b32 v79, v14 offset:396
	ds_read_b32 v80, v14 offset:528
	ds_read_b32 v81, v14 offset:660
	ds_read_b32 v82, v14 offset:792
	ds_read_b32 v83, v14 offset:924
	ds_read_b32 v84, v14 offset:64
	ds_read_b32 v85, v14 offset:196
	ds_read_b32 v86, v14 offset:328
	ds_read_b32 v87, v14 offset:460
	ds_read_b32 v88, v14 offset:592
	ds_read_b32 v89, v14 offset:724
	ds_read_b32 v90, v14 offset:856
	ds_read_b32 v91, v14 offset:988
	s_cmp_eq_u32 s24, 0
	s_cbranch_scc1 .Lpt_noB3
	ds_read_b32 v92, v14 offset:4224
	ds_read_b32 v93, v14 offset:4356
	ds_read_b32 v94, v14 offset:4488
	ds_read_b32 v95, v14 offset:4620
	ds_read_b32 v96, v14 offset:4752
	ds_read_b32 v97, v14 offset:4884
	ds_read_b32 v98, v14 offset:5016
	ds_read_b32 v99, v14 offset:5148
	ds_read_b32 v100, v14 offset:4288
	ds_read_b32 v101, v14 offset:4420
	ds_read_b32 v102, v14 offset:4552
	ds_read_b32 v103, v14 offset:4684
	ds_read_b32 v104, v14 offset:4816
	ds_read_b32 v105, v14 offset:4948
	ds_read_b32 v106, v14 offset:5080
	ds_read_b32 v107, v14 offset:5212
.Lpt_noB3:
	s_waitcnt lgkmcnt(0)
	v_cvt_pk_bf16_f32 v76, v76, v77
	v_cvt_pk_bf16_f32 v77, v78, v79
	v_cvt_pk_bf16_f32 v78, v80, v81
	v_cvt_pk_bf16_f32 v79, v82, v83
	global_store_dwordx4 v4, v[76:79], s[4:5]
	v_cvt_pk_bf16_f32 v84, v84, v85
	v_cvt_pk_bf16_f32 v85, v86, v87
	v_cvt_pk_bf16_f32 v86, v88, v89
	v_cvt_pk_bf16_f32 v87, v90, v91
	global_store_dwordx4 v5, v[84:87], s[4:5]
	s_cmp_eq_u32 s24, 0
	s_cbranch_scc1 .Lpt_noB4
	v_cvt_pk_bf16_f32 v92, v92, v93
	v_cvt_pk_bf16_f32 v93, v94, v95
	v_cvt_pk_bf16_f32 v94, v96, v97
	v_cvt_pk_bf16_f32 v95, v98, v99
	global_store_dwordx4 v7, v[92:95], s[14:15]
	v_cvt_pk_bf16_f32 v100, v100, v101
	v_cvt_pk_bf16_f32 v101, v102, v103
	v_cvt_pk_bf16_f32 v102, v104, v105
	v_cvt_pk_bf16_f32 v103, v106, v107
	global_store_dwordx4 v8, v[100:103], s[14:15]
.Lpt_noB4:
	s_lshl_b32 s9, s21, 1
	s_add_u32 s20, s20, s9
	s_cmpk_lt_u32 s20, 0x2d00
	s_cbranch_scc1 .Lpt_loop
; __device__ __forceinline__ void prep_phase(const Params& p, char* lds) {
;     ...
;     float* scr = (float*)(lds + wid * 8704);
;     constexpr int I_IN = 32 * 104, I_GLU = 16 * 64, I_ATT = 16 * 32, I_O = 32 * 32, I_UP = 32 * 176, I_DN = 88 * 32;
;     constexpr int NIT = I_IN + I_GLU + I_ATT + I_O + I_UP + I_DN;
;     for (int it = gw; it < NIT; it += NGW) {
;       int r = it;
;       if (r < I_IN) { transpose_item<0>(p.in[7], 1024, DIN, (bf16_t*)(ws + OFF_WIN), 0, scr, r, lane); continue; } r -= I_IN;
;       if (r < I_GLU) { transpose_item<1>(p.in[16], 512, 2048, (bf16_t*)(ws + OFF_WGLU), 1024, scr, r, lane); continue; } r -= I_GLU;
;       if (r < I_ATT) { transpose_item<0>(p.in[18], 512, 1024, (bf16_t*)(ws + OFF_WATT), 0, scr, r, lane); continue; } r -= I_ATT;
;       if (r < I_O) { transpose_item<0>(p.in[19], 1024, 1024, (bf16_t*)(ws + OFF_WO), 0, scr, r, lane); continue; } r -= I_O;
;       if (r < I_UP) { transpose_item<1>(p.in[22], 1024, 5632, (bf16_t*)(ws + OFF_WUP), DFF, scr, r, lane); continue; } r -= I_UP;
;       transpose_item<0>(p.in[25], DFF, 1024, (bf16_t*)(ws + OFF_WDN), 0, scr, r, lane);
;     }
.Lpt_done:
	s_waitcnt lgkmcnt(0)
	v_readlane_b32 s0, v246, 0
	v_readlane_b32 s1, v246, 1
	v_readlane_b32 s2, v246, 2
	v_readlane_b32 s3, v246, 3
	v_readlane_b32 s4, v246, 4
	v_readlane_b32 s5, v246, 5
	v_readlane_b32 s6, v246, 6
	v_readlane_b32 s7, v246, 7
	v_readlane_b32 s8, v246, 8
	v_readlane_b32 s9, v246, 9
	v_readlane_b32 s10, v246, 10
	v_readlane_b32 s11, v246, 11
	v_readlane_b32 s12, v246, 12
	v_readlane_b32 s13, v246, 13
	v_readlane_b32 s14, v246, 14
	v_readlane_b32 s15, v246, 15
	v_readlane_b32 s16, v246, 16
	v_readlane_b32 s17, v246, 17
	v_readlane_b32 s18, v246, 18
	v_readlane_b32 s19, v246, 19
	v_readlane_b32 s20, v246, 20
	v_readlane_b32 s21, v246, 21
	v_readlane_b32 s22, v246, 22
	v_readlane_b32 s23, v246, 23
	v_readlane_b32 s24, v246, 24
	v_readlane_b32 s25, v246, 25
	v_readlane_b32 s26, v246, 26
	v_readlane_b32 s27, v246, 27
	v_readlane_b32 s28, v246, 28
	v_readlane_b32 s29, v246, 29
	v_readlane_b32 s30, v246, 30
	v_readlane_b32 s31, v246, 31
	s_movk_i32 s0, 0x3800
	v_cmp_gt_i32_e32 vcc, s0, v182
	s_and_saveexec_b64 s[0:1], vcc
	s_branch .LBB0_40
	s_movk_i32 s3, 0x2200
	v_lshrrev_b32_e32 v45, 2, v184
	v_and_b32_e32 v3, 24, v43
	v_and_b32_e32 v4, 16, v0
	v_readlane_b32 s4, v244, 0
	v_mad_u32_u24 v1, v183, s3, 0
	v_lshlrev_b32_e32 v28, 2, v135
	v_mul_u32_u24_e32 v8, 0x84, v3
	v_and_or_b32 v9, v45, 3, v4
	v_lshlrev_b32_e32 v4, 1, v3
	v_mov_b32_e32 v5, 0
	v_readlane_b32 s5, v244, 1
	v_readlane_b32 s6, v244, 2
	v_readlane_b32 s7, v244, 3
	v_and_b32_e32 v3, 60, v184
	v_or_b32_e32 v49, 16, v45
	v_add_u32_e32 v44, v1, v28
	v_lshl_add_u64 v[16:17], s[6:7], 0, v[4:5]
	s_mov_b64 s[4:5], 0xdc80000
	v_add3_u32 v46, v1, v8, v3
	v_lshrrev_b32_e32 v1, 1, v49
	v_lshl_add_u64 v[6:7], v[16:17], 0, s[4:5]
	v_and_b32_e32 v47, 4, v134
	v_and_b32_e32 v50, 12, v1
	s_mov_b64 s[4:5], 0xd180000
	v_or_b32_e32 v48, v9, v47
	v_or_b32_e32 v51, v50, v9
	v_lshl_add_u64 v[8:9], v[16:17], 0, s[4:5]
	s_mov_b64 s[4:5], 0xcf80000
	v_lshl_add_u64 v[10:11], v[16:17], 0, s[4:5]
	s_mov_b64 s[4:5], 0xce80000
	v_lshl_add_u64 v[12:13], v[16:17], 0, s[4:5]
	s_mov_b64 s[4:5], 0xcc80000
	v_lshl_add_u64 v[14:15], v[16:17], 0, s[4:5]
	s_mov_b64 s[4:5], 0xc600000
	v_lshl_add_u64 v[16:17], v[16:17], 0, s[4:5]
	v_readlane_b32 s4, v244, 4
	v_mov_b32_e32 v29, v5
	v_readlane_b32 s5, v244, 5
	v_readlane_b32 s6, v244, 6
	v_readlane_b32 s7, v244, 7
	v_readlane_b32 s8, v244, 8
	v_readlane_b32 s9, v244, 9
	v_readlane_b32 s10, v244, 10
	v_readlane_b32 s11, v244, 11
	v_lshl_add_u64 v[18:19], s[6:7], 0, v[28:29]
	v_readlane_b32 s4, v244, 35
	v_readlane_b32 s5, v244, 36
	v_readlane_b32 s6, v244, 37
	v_readlane_b32 s7, v244, 38
	v_readlane_b32 s8, v244, 39
	v_readlane_b32 s9, v244, 40
	v_readlane_b32 s10, v244, 41
	v_readlane_b32 s11, v244, 42
	v_readlane_b32 s12, v244, 43
	v_readlane_b32 s13, v244, 44
	v_readlane_b32 s14, v244, 45
	v_readlane_b32 s15, v244, 46
	v_readlane_b32 s16, v244, 47
	v_readlane_b32 s17, v244, 48
	v_readlane_b32 s18, v244, 49
	v_readlane_b32 s19, v244, 50
	v_lshrrev_b32_e32 v2, 5, v184
	v_lshl_add_u64 v[20:21], s[16:17], 0, v[28:29]
	v_lshl_add_u64 v[22:23], s[10:11], 0, v[28:29]
	v_lshl_add_u64 v[24:25], s[8:9], 0, v[28:29]
	v_lshl_add_u64 v[26:27], s[4:5], 0, v[28:29]
	v_readlane_b32 s4, v244, 14
	v_readlane_b32 s5, v244, 15
	v_readlane_b32 s16, v244, 26
	v_readlane_b32 s17, v244, 27
	v_readlane_b32 s18, v244, 28
	v_readlane_b32 s19, v244, 29
	v_or_b32_e32 v1, 2, v2
	v_or_b32_e32 v3, 6, v2
	v_or_b32_e32 v30, 4, v2
	v_or_b32_e32 v31, 10, v2
	v_or_b32_e32 v32, 8, v2
	v_or_b32_e32 v34, 12, v2
	v_or_b32_e32 v33, 14, v2
	v_or_b32_e32 v36, 16, v2
	v_or_b32_e32 v35, 18, v2
	v_or_b32_e32 v38, 20, v2
	v_or_b32_e32 v37, 22, v2
	v_or_b32_e32 v40, 24, v2
	v_or_b32_e32 v39, 26, v2
	v_or_b32_e32 v42, 28, v2
	v_or_b32_e32 v41, 30, v2
	v_lshl_add_u64 v[28:29], s[18:19], 0, v[28:29]
	v_mul_u32_u24_e32 v52, 0x84, v2
	v_mul_u32_u24_e32 v53, 0x84, v1
	v_mul_u32_u24_e32 v54, 0x84, v30
	v_mul_u32_u24_e32 v55, 0x84, v3
	s_mov_b64 s[4:5], 0
	s_movk_i32 s3, 0xcff
	s_movk_i32 s16, 0x10ff
	s_movk_i32 s17, 0x12ff
	s_movk_i32 s18, 0x16ff
	s_movk_i32 s19, 0x2cff
	s_movk_i32 s20, 0xb00
	s_movk_i32 s21, 0x63
	s_movk_i32 s22, 0x400
	s_mov_b32 s23, 0x4ec4ec4f
	s_movk_i32 s24, 0xff98
	s_movk_i32 s25, 0x3400
	s_movk_i32 s26, 0x2cff
	v_mul_u32_u24_e32 v56, 0x84, v32
	v_mul_u32_u24_e32 v57, 0x84, v31
	v_mul_u32_u24_e32 v58, 0x84, v34
	v_mul_u32_u24_e32 v59, 0x84, v33
	v_mul_u32_u24_e32 v60, 0x84, v36
	v_mul_u32_u24_e32 v61, 0x84, v35
	v_mul_u32_u24_e32 v62, 0x84, v38
	v_mul_u32_u24_e32 v63, 0x84, v37
	v_mul_u32_u24_e32 v64, 0x84, v40
	v_mul_u32_u24_e32 v65, 0x84, v39
	v_mul_u32_u24_e32 v66, 0x84, v42
	v_mul_u32_u24_e32 v67, 0x84, v41
	v_mov_b32_e32 v68, 0xfffff500
	v_mov_b32_e32 v69, 0xfffffc00
	v_mov_b32_e32 v70, v182
	v_readlane_b32 s6, v244, 16
	v_readlane_b32 s7, v244, 17
	v_readlane_b32 s8, v244, 18
	v_readlane_b32 s9, v244, 19
	v_readlane_b32 s10, v244, 20
	v_readlane_b32 s11, v244, 21
	v_readlane_b32 s12, v244, 22
	v_readlane_b32 s13, v244, 23
	v_readlane_b32 s14, v244, 24
	v_readlane_b32 s15, v244, 25
	s_branch .LBB0_20
